# SGU item: 8 early loads of the gate rows (u tile) before the MFMA loop so the in-loop dependent loads hit cache
# baseline (speedup 1.0000x reference)
.LBB0_249:
	s_or_b64 exec, exec, s[8:9]
	v_lshl_add_u32 v50, v73, 1, 0
	s_movk_i32 s14, 0x110
	v_cvt_pk_bf16_f32 v22, v22, v23
	v_cvt_pk_bf16_f32 v23, v24, v25
	v_cvt_pk_bf16_f32 v24, v18, v19
	s_waitcnt lgkmcnt(1)
	v_mad_u64_u32 v[18:19], s[8:9], v74, s14, v[50:51]
	v_cvt_pk_bf16_f32 v25, v20, v21
	ds_write_b128 v18, v[22:25]
	v_mad_u64_u32 v[22:23], s[8:9], v71, s14, v[50:51]
	v_cvt_pk_bf16_f32 v18, v30, v31
	v_cvt_pk_bf16_f32 v19, v32, v33
	v_cvt_pk_bf16_f32 v20, v26, v27
	v_cvt_pk_bf16_f32 v21, v28, v29
	ds_write_b128 v22, v[18:21]
	v_mad_u64_u32 v[22:23], s[8:9], v70, s14, v[50:51]
	v_cvt_pk_bf16_f32 v18, v38, v39
	v_cvt_pk_bf16_f32 v19, v40, v41
	v_cvt_pk_bf16_f32 v20, v34, v35
	v_cvt_pk_bf16_f32 v21, v36, v37
	ds_write_b128 v22, v[18:21]
	v_mad_u64_u32 v[22:23], s[8:9], v69, s14, v[50:51]
	v_cvt_pk_bf16_f32 v18, v46, v47
	v_cvt_pk_bf16_f32 v19, v48, v49
	v_cvt_pk_bf16_f32 v20, v42, v43
	v_cvt_pk_bf16_f32 v21, v44, v45
	ds_write_b128 v22, v[18:21]
	s_waitcnt lgkmcnt(0)
	s_barrier
	s_load_dwordx2 s[8:9], s[0:1], 0xa0
	v_readlane_b32 s16, v255, 38
	v_readlane_b32 s17, v255, 39
	s_lshl_b64 s[12:13], s[16:17], 2
	v_and_b32_e32 v26, 0xffff0000, v14
	s_waitcnt lgkmcnt(0)
	s_add_u32 s8, s8, s12
	s_addc_u32 s9, s9, s13
	s_lshl_b32 s12, s7, 2
	s_add_u32 s8, s8, s12
	s_addc_u32 s9, s9, 0
	global_load_dwordx4 v[22:25], v0, s[8:9]
	global_load_dwordx4 v[18:21], v0, s[8:9] offset:16
	s_add_i32 s12, 0, 0x20000
	v_lshlrev_b32_e32 v0, 16, v14
	v_lshl_add_u32 v14, v74, 2, s12
	v_lshlrev_b32_e32 v27, 16, v15
	v_and_b32_e32 v28, 0xffff0000, v15
	ds_read2st64_b32 v[14:15], v14 offset1:2
	v_lshlrev_b32_e32 v29, 16, v16
	v_and_b32_e32 v16, 0xffff0000, v16
	v_lshlrev_b32_e32 v30, 16, v17
	v_and_b32_e32 v17, 0xffff0000, v17
	s_waitcnt lgkmcnt(0)
	v_sub_f32_e32 v0, v0, v14
	v_sub_f32_e32 v26, v26, v14
	v_sub_f32_e32 v27, v27, v14
	v_sub_f32_e32 v28, v28, v14
	v_sub_f32_e32 v29, v29, v14
	v_sub_f32_e32 v16, v16, v14
	v_sub_f32_e32 v30, v30, v14
	v_sub_f32_e32 v14, v17, v14
	v_mul_f32_e32 v0, v15, v0
	v_mul_f32_e32 v17, v15, v26
	v_mul_f32_e32 v26, v15, v27
	v_mul_f32_e32 v27, v15, v28
	v_mul_f32_e32 v28, v15, v29
	v_mul_f32_e32 v16, v15, v16
	v_mul_f32_e32 v29, v15, v30
	v_mul_f32_e32 v14, v15, v14
	v_lshlrev_b32_e32 v31, 1, v74
	v_mul_u32_u24_e32 v32, 0x110, v73
	v_add3_u32 v31, 0, v31, v32
	s_load_dwordx2 s[8:9], s[0:1], 0xb0
	s_add_i32 s11, s11, 16
	s_lshl_b32 s6, s6, 7
	s_waitcnt vmcnt(1)
	v_mul_f32_e32 v0, v22, v0
	v_mul_f32_e32 v15, v23, v17
	v_mul_f32_e32 v17, v24, v26
	v_mul_f32_e32 v26, v25, v27
	s_waitcnt vmcnt(0)
	v_mul_f32_e32 v27, v18, v28
	v_mul_f32_e32 v16, v19, v16
	v_mul_f32_e32 v28, v20, v29
	v_mul_f32_e32 v29, v21, v14
	v_bfe_u32 v14, v0, 16, 1
	v_bfe_u32 v30, v15, 16, 1
	v_bfe_u32 v33, v17, 16, 1
	v_bfe_u32 v34, v26, 16, 1
	v_bfe_u32 v35, v27, 16, 1
	v_bfe_u32 v36, v16, 16, 1
	v_add3_u32 v0, v0, v14, s90
	v_add3_u32 v14, v15, v30, s90
	v_add3_u32 v15, v17, v33, s90
	v_add3_u32 v17, v26, v34, s90
	v_add3_u32 v26, v27, v35, s90
	v_add3_u32 v16, v16, v36, s90
	ds_write_b16_d16_hi v31, v0 offset:34816
	ds_write_b16_d16_hi v31, v14 offset:35088
	ds_write_b16_d16_hi v31, v15 offset:35360
	ds_write_b16_d16_hi v31, v17 offset:35632
	ds_write_b16_d16_hi v31, v26 offset:35904
	ds_write_b16_d16_hi v31, v16 offset:36176
	v_bfe_u32 v0, v28, 16, 1
	v_add3_u32 v0, v28, v0, s90
	ds_write_b16_d16_hi v31, v0 offset:36448
	v_lshl_add_u32 v0, v71, 2, s12
	ds_read2st64_b32 v[14:15], v0 offset1:2
	v_bfe_u32 v0, v29, 16, 1
	v_add3_u32 v0, v29, v0, s90
	ds_write_b16_d16_hi v31, v0 offset:36720
	v_lshlrev_b32_e32 v0, 16, v10
	s_waitcnt lgkmcnt(0)
	v_sub_f32_e32 v0, v0, v14
	v_mul_f32_e32 v0, v15, v0
	v_and_b32_e32 v10, 0xffff0000, v10
	v_lshlrev_b32_e32 v16, 16, v11
	v_and_b32_e32 v11, 0xffff0000, v11
	v_lshlrev_b32_e32 v17, 16, v12
	v_and_b32_e32 v12, 0xffff0000, v12
	v_lshlrev_b32_e32 v26, 16, v13
	v_and_b32_e32 v13, 0xffff0000, v13
	v_mul_f32_e32 v0, v22, v0
	v_sub_f32_e32 v10, v10, v14
	v_sub_f32_e32 v16, v16, v14
	v_sub_f32_e32 v11, v11, v14
	v_sub_f32_e32 v17, v17, v14
	v_sub_f32_e32 v12, v12, v14
	v_sub_f32_e32 v26, v26, v14
	v_sub_f32_e32 v13, v13, v14
	v_mul_f32_e32 v10, v15, v10
	v_mul_f32_e32 v16, v15, v16
	v_mul_f32_e32 v11, v15, v11
	v_mul_f32_e32 v17, v15, v17
	v_mul_f32_e32 v12, v15, v12
	v_mul_f32_e32 v26, v15, v26
	v_mul_f32_e32 v13, v15, v13
	v_lshlrev_b32_e32 v14, 1, v71
	v_bfe_u32 v15, v0, 16, 1
	v_mul_f32_e32 v10, v23, v10
	v_add3_u32 v0, v0, v15, s90
	v_add3_u32 v14, 0, v14, v32
	ds_write_b16_d16_hi v14, v0 offset:34816
	v_bfe_u32 v0, v10, 16, 1
	v_mul_f32_e32 v16, v24, v16
	v_add3_u32 v0, v10, v0, s90
	ds_write_b16_d16_hi v14, v0 offset:35088
	v_bfe_u32 v0, v16, 16, 1
	v_mul_f32_e32 v11, v25, v11
	v_add3_u32 v0, v16, v0, s90
	ds_write_b16_d16_hi v14, v0 offset:35360
	v_bfe_u32 v0, v11, 16, 1
	v_mul_f32_e32 v17, v18, v17
	v_add3_u32 v0, v11, v0, s90
	ds_write_b16_d16_hi v14, v0 offset:35632
	v_bfe_u32 v0, v17, 16, 1
	v_mul_f32_e32 v12, v19, v12
	v_add3_u32 v0, v17, v0, s90
	ds_write_b16_d16_hi v14, v0 offset:35904
	v_bfe_u32 v0, v12, 16, 1
	v_mul_f32_e32 v26, v20, v26
	v_add3_u32 v0, v12, v0, s90
	ds_write_b16_d16_hi v14, v0 offset:36176
	v_bfe_u32 v0, v26, 16, 1
	v_add3_u32 v0, v26, v0, s90
	ds_write_b16_d16_hi v14, v0 offset:36448
	v_lshl_add_u32 v0, v70, 2, s12
	ds_read2st64_b32 v[10:11], v0 offset1:2
	v_mul_f32_e32 v13, v21, v13
	v_bfe_u32 v0, v13, 16, 1
	v_add3_u32 v0, v13, v0, s90
	ds_write_b16_d16_hi v14, v0 offset:36720
	v_lshlrev_b32_e32 v0, 16, v6
	s_waitcnt lgkmcnt(1)
	v_sub_f32_e32 v0, v0, v10
	v_mul_f32_e32 v0, v11, v0
	v_and_b32_e32 v6, 0xffff0000, v6
	v_lshlrev_b32_e32 v12, 16, v7
	v_and_b32_e32 v7, 0xffff0000, v7
	v_lshlrev_b32_e32 v13, 16, v8
	v_and_b32_e32 v8, 0xffff0000, v8
	v_lshlrev_b32_e32 v14, 16, v9
	v_and_b32_e32 v9, 0xffff0000, v9
	v_mul_f32_e32 v0, v22, v0
	v_sub_f32_e32 v6, v6, v10
	v_sub_f32_e32 v12, v12, v10
	v_sub_f32_e32 v7, v7, v10
	v_sub_f32_e32 v13, v13, v10
	v_sub_f32_e32 v8, v8, v10
	v_sub_f32_e32 v14, v14, v10
	v_sub_f32_e32 v9, v9, v10
	v_mul_f32_e32 v6, v11, v6
	v_mul_f32_e32 v12, v11, v12
	v_mul_f32_e32 v7, v11, v7
	v_mul_f32_e32 v13, v11, v13
	v_mul_f32_e32 v8, v11, v8
	v_mul_f32_e32 v14, v11, v14
	v_mul_f32_e32 v9, v11, v9
	v_lshlrev_b32_e32 v10, 1, v70
	v_bfe_u32 v11, v0, 16, 1
	v_mul_f32_e32 v6, v23, v6
	v_add3_u32 v0, v0, v11, s90
	v_add3_u32 v10, 0, v10, v32
	ds_write_b16_d16_hi v10, v0 offset:34816
	v_bfe_u32 v0, v6, 16, 1
	v_mul_f32_e32 v12, v24, v12
	v_add3_u32 v0, v6, v0, s90
	ds_write_b16_d16_hi v10, v0 offset:35088
	v_bfe_u32 v0, v12, 16, 1
	v_mul_f32_e32 v7, v25, v7
	v_add3_u32 v0, v12, v0, s90
	ds_write_b16_d16_hi v10, v0 offset:35360
	v_bfe_u32 v0, v7, 16, 1
	v_mul_f32_e32 v13, v18, v13
	v_add3_u32 v0, v7, v0, s90
	ds_write_b16_d16_hi v10, v0 offset:35632
	v_bfe_u32 v0, v13, 16, 1
	v_mul_f32_e32 v8, v19, v8
	v_add3_u32 v0, v13, v0, s90
	ds_write_b16_d16_hi v10, v0 offset:35904
	v_bfe_u32 v0, v8, 16, 1
	v_mul_f32_e32 v14, v20, v14
	v_add3_u32 v0, v8, v0, s90
	ds_write_b16_d16_hi v10, v0 offset:36176
	v_bfe_u32 v0, v14, 16, 1
	v_add3_u32 v0, v14, v0, s90
	ds_write_b16_d16_hi v10, v0 offset:36448
	v_lshl_add_u32 v0, v69, 2, s12
	ds_read2st64_b32 v[6:7], v0 offset1:2
	v_mul_f32_e32 v9, v21, v9
	v_bfe_u32 v0, v9, 16, 1
	v_add3_u32 v0, v9, v0, s90
	ds_write_b16_d16_hi v10, v0 offset:36720
	v_lshlrev_b32_e32 v0, 16, v2
	s_waitcnt lgkmcnt(1)
	v_sub_f32_e32 v0, v0, v6
	v_mul_f32_e32 v0, v7, v0
	v_and_b32_e32 v2, 0xffff0000, v2
	v_lshlrev_b32_e32 v8, 16, v3
	v_and_b32_e32 v3, 0xffff0000, v3
	v_lshlrev_b32_e32 v9, 16, v4
	v_and_b32_e32 v4, 0xffff0000, v4
	v_lshlrev_b32_e32 v10, 16, v5
	v_and_b32_e32 v5, 0xffff0000, v5
	v_mul_f32_e32 v0, v22, v0
	v_sub_f32_e32 v2, v2, v6
	v_sub_f32_e32 v8, v8, v6
	v_sub_f32_e32 v3, v3, v6
	v_sub_f32_e32 v9, v9, v6
	v_sub_f32_e32 v4, v4, v6
	v_sub_f32_e32 v10, v10, v6
	v_sub_f32_e32 v5, v5, v6
	v_mul_f32_e32 v2, v7, v2
	v_mul_f32_e32 v8, v7, v8
	v_mul_f32_e32 v3, v7, v3
	v_mul_f32_e32 v9, v7, v9
	v_mul_f32_e32 v4, v7, v4
	v_mul_f32_e32 v10, v7, v10
	v_mul_f32_e32 v5, v7, v5
	v_lshlrev_b32_e32 v6, 1, v69
	v_bfe_u32 v7, v0, 16, 1
	v_mul_f32_e32 v2, v23, v2
	v_add3_u32 v0, v0, v7, s90
	v_add3_u32 v6, 0, v6, v32
	ds_write_b16_d16_hi v6, v0 offset:34816
	v_bfe_u32 v0, v2, 16, 1
	v_mul_f32_e32 v8, v24, v8
	v_add3_u32 v0, v2, v0, s90
	ds_write_b16_d16_hi v6, v0 offset:35088
	v_bfe_u32 v0, v8, 16, 1
	v_mul_f32_e32 v3, v25, v3
	v_add3_u32 v0, v8, v0, s90
	ds_write_b16_d16_hi v6, v0 offset:35360
	v_bfe_u32 v0, v3, 16, 1
	v_mul_f32_e32 v9, v18, v9
	v_add3_u32 v0, v3, v0, s90
	ds_write_b16_d16_hi v6, v0 offset:35632
	v_bfe_u32 v0, v9, 16, 1
	v_mul_f32_e32 v4, v19, v4
	v_add3_u32 v0, v9, v0, s90
	ds_write_b16_d16_hi v6, v0 offset:35904
	v_bfe_u32 v0, v4, 16, 1
	v_mul_f32_e32 v10, v20, v10
	v_add3_u32 v0, v4, v0, s90
	ds_write_b16_d16_hi v6, v0 offset:36176
	v_bfe_u32 v0, v10, 16, 1
	v_mul_f32_e32 v5, v21, v5
	v_add3_u32 v0, v10, v0, s90
	ds_write_b16_d16_hi v6, v0 offset:36448
	v_bfe_u32 v0, v5, 16, 1
	v_add3_u32 v0, v5, v0, s90
	ds_write_b16_d16_hi v6, v0 offset:36720
	v_bfe_u32 v18, v68, 4, 2
	v_bfi_b32 v0, -16, v72, v68
	v_and_b32_e32 v19, -16, v72
	v_mul_lo_u32 v0, v0, s14
	v_lshlrev_b32_e32 v22, 4, v18
	v_add3_u32 v0, 0, v0, v22
	v_lshl_or_b32 v18, v18, 2, v19
	s_waitcnt lgkmcnt(0)
	s_barrier
	v_and_b32_e32 v23, 15, v68
	ds_read_b128 v[2:5], v0 offset:34816
	ds_read_b128 v[6:9], v0 offset:34880
	ds_read_b128 v[10:13], v0 offset:34944
	ds_read_b128 v[14:17], v0 offset:35008
	v_mov_b32_e32 v0, s20
	v_ashrrev_i32_e32 v19, 31, v18
	v_lshl_add_u64 v[24:25], v[18:19], 1, v[0:1]
	v_add_lshl_u32 v0, s11, v23, 11
	s_ashr_i32 s12, s6, 31
	v_or_b32_e32 v20, s6, v23
	v_lshl_add_u64 v[18:19], v[24:25], 0, v[0:1]
	v_mul_u32_u24_e32 v0, 0x110, v23
	s_add_i32 s6, s16, s7
	v_add3_u32 v26, v0, v22, 0
	v_add_u32_e32 v22, s6, v23
	s_lshl_b32 s6, s10, 16
	s_and_b32 s6, s6, 0x3fc0000
	v_mov_b32_e32 v21, s12
	v_lshl_or_b32 v0, v23, 11, s6
	v_lshl_add_u64 v[20:21], v[20:21], 2, s[8:9]
	v_lshl_add_u64 v[24:25], v[24:25], 0, v[0:1]
	v_lshl_add_u64 v[18:19], s[64:65], 0, v[18:19]
	v_lshl_add_u64 v[20:21], v[20:21], 0, 64
	v_lshl_add_u64 v[24:25], s[64:65], 0, v[24:25]
	s_mov_b64 s[6:7], 0
	s_mov_b32 s98, 0xc200000
	s_mov_b32 s99, 0
	v_lshl_add_u64 v[236:237], v[24:25], 0, s[98:99]
	global_load_dword v238, v[236:237], off
	v_lshl_add_u64 v[236:237], v[18:19], 0, s[98:99]
	global_load_dword v239, v[236:237], off
	s_add_u32 s98, s98, 0x10000
	v_lshl_add_u64 v[236:237], v[24:25], 0, s[98:99]
	global_load_dword v240, v[236:237], off
	v_lshl_add_u64 v[236:237], v[18:19], 0, s[98:99]
	global_load_dword v241, v[236:237], off
	s_add_u32 s98, s98, 0x10000
	v_lshl_add_u64 v[236:237], v[24:25], 0, s[98:99]
	global_load_dword v242, v[236:237], off
	v_lshl_add_u64 v[236:237], v[18:19], 0, s[98:99]
	global_load_dword v243, v[236:237], off
	s_add_u32 s98, s98, 0x10000
	v_lshl_add_u64 v[236:237], v[24:25], 0, s[98:99]
	global_load_dword v244, v[236:237], off
	v_lshl_add_u64 v[236:237], v[18:19], 0, s[98:99]
	global_load_dword v245, v[236:237], off
